# norm phase: first row loads issued right after the weight-pointer load (counted vmcnt), in flight during pointer->weight->LDS staging chain (from v35)
# speedup vs baseline: 1.0002x; 1.0002x over previous
; #define LAS __attribute__((address_space(3)))
; #define INP(a, i) inp_(a, i)
; DI void norm_phase(unsigned char* lds, const Ctx& a, const Op& d) {
;     ...
;         const float* gg = (d.idx == 1 ? INP(a, 2) : INP(a, 1)) + d.layer * DM;
;         __syncthreads();
;         for (int i = tid * 4; i < DM; i += NTHREADS * 4) *(LAS f32x4*)(g + i) = *(const f32x4*)(gg + i);
;         __syncthreads();
;     }
;     bf16_t* H = (bf16_t*)(a.ws + WS_AR);
;     f32x4 nx[8];
;     if (gw < MTOK) load_row(d.xin + (size_t)gw * DM, lane, nx);
.LBB0_517:
	s_andn2_b64 vcc, exec, s[0:1]
	s_cbranch_vccnz .LBB0_531
	v_readlane_b32 s0, v231, 19
	s_cmp_lg_u32 s0, 1
	s_mov_b64 s[0:1], -1
	s_waitcnt vmcnt(0)
	v_mbcnt_lo_u32_b32 v2, -1, 0
	v_mbcnt_hi_u32_b32 v2, -1, v2
	s_cbranch_scc0 .LBB0_520
	v_mov_b64_e32 v[0:1], s[58:59]
	global_load_dwordx2 v[0:1], v[0:1], off offset:8
	v_add_u32_e32 v70, s80, v2
	v_ashrrev_i32_e32 v70, 6, v70
	v_add_u32_e32 v64, s40, v70
	v_ashrrev_i32_e32 v65, 31, v64
	v_lshlrev_b64 v[70:71], 13, v[64:65]
	v_lshlrev_b32_e32 v72, 4, v2
	v_lshl_add_u64 v[70:71], s[72:73], 0, v[70:71]
	v_and_b32_e32 v72, 0x3f0, v72
	v_mov_b32_e32 v73, 0
	v_lshl_add_u64 v[70:71], v[70:71], 0, v[72:73]
	global_load_dwordx4 v[60:63], v[70:71], off
	global_load_dwordx4 v[56:59], v[70:71], off offset:1024
	global_load_dwordx4 v[52:55], v[70:71], off offset:2048
	global_load_dwordx4 v[44:47], v[70:71], off offset:3072
	v_mov_b32_e32 v72, 0x1000
	v_lshl_add_u64 v[70:71], v[70:71], 0, v[72:73]
	global_load_dwordx4 v[28:31], v[70:71], off
	global_load_dwordx4 v[24:27], v[70:71], off offset:1024
	global_load_dwordx4 v[20:23], v[70:71], off offset:2048
	global_load_dwordx4 v[16:19], v[70:71], off offset:3072
	s_mov_b64 s[0:1], 0
	s_waitcnt vmcnt(8) lgkmcnt(0)
	v_readfirstlane_b32 s4, v0
	v_readfirstlane_b32 s5, v1
.LBB0_520:
	s_andn2_b64 vcc, exec, s[0:1]
	s_cbranch_vccnz .LBB0_522
	v_mov_b64_e32 v[0:1], s[58:59]
	global_load_dwordx2 v[0:1], v[0:1], off offset:16
	v_add_u32_e32 v70, s80, v2
	v_ashrrev_i32_e32 v70, 6, v70
	v_add_u32_e32 v64, s40, v70
	v_ashrrev_i32_e32 v65, 31, v64
	v_lshlrev_b64 v[70:71], 13, v[64:65]
	v_lshlrev_b32_e32 v72, 4, v2
	v_lshl_add_u64 v[70:71], s[72:73], 0, v[70:71]
	v_and_b32_e32 v72, 0x3f0, v72
	v_mov_b32_e32 v73, 0
	v_lshl_add_u64 v[70:71], v[70:71], 0, v[72:73]
	global_load_dwordx4 v[60:63], v[70:71], off
	global_load_dwordx4 v[56:59], v[70:71], off offset:1024
	global_load_dwordx4 v[52:55], v[70:71], off offset:2048
	global_load_dwordx4 v[44:47], v[70:71], off offset:3072
	v_mov_b32_e32 v72, 0x1000
	v_lshl_add_u64 v[70:71], v[70:71], 0, v[72:73]
	global_load_dwordx4 v[28:31], v[70:71], off
	global_load_dwordx4 v[24:27], v[70:71], off offset:1024
	global_load_dwordx4 v[20:23], v[70:71], off offset:2048
	global_load_dwordx4 v[16:19], v[70:71], off offset:3072
	s_waitcnt vmcnt(8) lgkmcnt(0)
	v_readfirstlane_b32 s4, v0
	v_readfirstlane_b32 s5, v1

; DI void norm_phase(unsigned char* lds, const Ctx& a, const Op& d) {
;     ...
;     if (gw < MTOK) load_row(d.xin + (size_t)gw * DM, lane, nx);
;     for (int m = gw; m < MTOK; m += NGW) {
;         f32x4 v[8];
; #pragma unroll
;         for (int j = 0; j < 8; ++j) v[j] = nx[j];
;         if (m + NGW < MTOK) load_row(d.xin + (size_t)(m + NGW) * DM, lane, nx);
;         finish_row(g, lane, v);
.LBB0_525:
	s_or_b64 exec, exec, s[0:1]
	v_ashrrev_i32_e32 v0, 6, v3
	v_add_u32_e32 v64, s40, v0
	s_movk_i32 s0, 0x4000
	v_cmp_gt_i32_e32 vcc, s0, v64
	s_waitcnt lgkmcnt(0)
	s_barrier
	s_and_saveexec_b64 s[6:7], vcc
	s_cbranch_execz .LBB0_530
	v_ashrrev_i32_e32 v65, 31, v64
	v_lshlrev_b64 v[0:1], 13, v[64:65]
	v_lshlrev_b32_e32 v3, 4, v2
	v_lshl_add_u64 v[0:1], s[72:73], 0, v[0:1]
	v_and_b32_e32 v96, 0x3f0, v3
	v_lshl_add_u64 v[0:1], v[0:1], 0, v[96:97]
	v_add_co_u32_e32 v0, vcc, 0x1000, v0
	v_and_b32_e32 v3, 1, v2
	s_nop 0
	v_addc_co_u32_e32 v1, vcc, 0, v1, vcc
	v_lshlrev_b32_e32 v2, 3, v2
	v_cmp_eq_u32_e64 s[0:1], 0, v3
	v_lshlrev_b64 v[0:1], 12, v[64:65]
	v_lshlrev_b32_e32 v3, 9, v3
	v_and_b32_e32 v2, 0x1f0, v2
	v_or3_b32 v0, v0, v3, v2
	v_lshl_add_u64 v[66:67], s[12:13], 0, v[0:1]
	v_add_u32_e32 v0, s16, v64
	v_ashrrev_i32_e32 v1, 31, v0
	v_lshlrev_b64 v[0:1], 13, v[0:1]
	v_or_b32_e32 v0, v0, v96
	s_ashr_i32 s17, s16, 31
	v_lshl_add_u64 v[68:69], s[72:73], 0, v[0:1]
	s_lshl_b64 s[8:9], s[16:17], 12
	s_lshl_b64 s[10:11], s[16:17], 13
	s_mov_b64 s[18:19], 0
	s_waitcnt vmcnt(0) lgkmcnt(0)
	v_mov_b64_e32 v[48:49], v[60:61]
	v_mov_b64_e32 v[40:41], v[56:57]
	v_mov_b64_e32 v[36:37], v[52:53]
	v_mov_b64_e32 v[32:33], v[44:45]
	v_mov_b64_e32 v[34:35], v[46:47]
	v_mov_b64_e32 v[38:39], v[54:55]
	v_mov_b64_e32 v[12:13], v[28:29]
	v_mov_b64_e32 v[8:9], v[24:25]
	v_mov_b64_e32 v[4:5], v[20:21]
	v_mov_b64_e32 v[0:1], v[16:17]
	v_mov_b64_e32 v[2:3], v[18:19]
	v_mov_b64_e32 v[6:7], v[22:23]
	v_mov_b64_e32 v[10:11], v[26:27]
	v_mov_b64_e32 v[14:15], v[30:31]
	v_mov_b64_e32 v[42:43], v[58:59]
	v_mov_b64_e32 v[50:51], v[62:63]
	s_branch .LBB0_528
